# v15 + attention loop edges: QK^T segment head (address VALU, -m accumulator init, visibility compare) moved in front of its barrier; rescale test shortened to v_cmp/s_cmp/one branch
# baseline (speedup 1.0000x reference)
.LBB0_1417:
	s_mul_i32 s17, s3, 0x6000
	s_add_i32 s0, s17, 0
	v_add_u32_e32 v16, s0, v213
	v_add_u32_e32 v17, v16, v214
	v_add_u32_e32 v221, v16, v215
	v_add_u32_e32 v234, v16, v216
	v_xor_b32_e32 v18, 0x80000000, v3
	v_mov_b32_e32 v19, v18
	v_mov_b32_e32 v20, v18
	v_mov_b32_e32 v21, v18
	v_mov_b32_e32 v22, v18
	v_mov_b32_e32 v23, v18
	v_mov_b32_e32 v24, v18
	v_mov_b32_e32 v25, v18
	v_mov_b32_e32 v26, v18
	v_mov_b32_e32 v27, v18
	v_mov_b32_e32 v28, v18
	v_mov_b32_e32 v29, v18
	v_mov_b32_e32 v30, v18
	v_mov_b32_e32 v31, v18
	v_mov_b32_e32 v32, v18
	v_mov_b32_e32 v33, v18
	s_cmp_le_u32 s16, s18
	s_cselect_b64 s[12:13], -1, 0
	s_cmp_gt_u32 s16, s18
	s_barrier
	s_cbranch_scc1 .LBB0_1419
	ds_read_b128 v[4:7], v17 offset:0
	ds_read_b128 v[8:11], v17 offset:12288
	ds_read_b128 v[12:15], v221 offset:0
	ds_read_b128 v[222:225], v221 offset:12288
	s_setprio 1
	ds_read_b128 v[226:229], v234 offset:0
	ds_read_b128 v[230:233], v234 offset:12288
	s_waitcnt lgkmcnt(4)
	v_mfma_f32_32x32x16_bf16 v[34:49], v[4:7], v[114:117], v[18:33]
	v_mfma_f32_32x32x16_bf16 v[18:33], v[8:11], v[114:117], v[18:33]
	v_add_u32_e32 v16, v16, v217
	ds_read_b128 v[4:7], v16 offset:0
	ds_read_b128 v[8:11], v16 offset:12288
	s_waitcnt lgkmcnt(4)
	v_mfma_f32_32x32x16_bf16 v[34:49], v[12:15], v[118:121], v[34:49]
	v_mfma_f32_32x32x16_bf16 v[18:33], v[222:225], v[118:121], v[18:33]
	ds_read_b128 v[12:15], v17 offset:4096
	ds_read_b128 v[222:225], v17 offset:16384
	s_waitcnt lgkmcnt(4)
	v_mfma_f32_32x32x16_bf16 v[34:49], v[226:229], v[122:125], v[34:49]
	v_mfma_f32_32x32x16_bf16 v[18:33], v[230:233], v[122:125], v[18:33]
	ds_read_b128 v[226:229], v221 offset:4096
	ds_read_b128 v[230:233], v221 offset:16384
	s_waitcnt lgkmcnt(4)
	v_mfma_f32_32x32x16_bf16 v[34:49], v[4:7], v[126:129], v[34:49]
	v_mfma_f32_32x32x16_bf16 v[18:33], v[8:11], v[126:129], v[18:33]
	ds_read_b128 v[4:7], v234 offset:4096
	ds_read_b128 v[8:11], v234 offset:16384
	s_waitcnt lgkmcnt(4)
	v_mfma_f32_32x32x16_bf16 v[34:49], v[12:15], v[130:133], v[34:49]
	v_mfma_f32_32x32x16_bf16 v[18:33], v[222:225], v[130:133], v[18:33]
	ds_read_b128 v[12:15], v16 offset:4096
	ds_read_b128 v[222:225], v16 offset:16384
	s_waitcnt lgkmcnt(4)
	v_mfma_f32_32x32x16_bf16 v[34:49], v[226:229], v[134:137], v[34:49]
	v_mfma_f32_32x32x16_bf16 v[18:33], v[230:233], v[134:137], v[18:33]
	ds_read_b128 v[226:229], v17 offset:8192
	ds_read_b128 v[230:233], v17 offset:20480
	s_waitcnt lgkmcnt(4)
	v_mfma_f32_32x32x16_bf16 v[34:49], v[4:7], v[138:141], v[34:49]
	v_mfma_f32_32x32x16_bf16 v[18:33], v[8:11], v[138:141], v[18:33]
	ds_read_b128 v[4:7], v221 offset:8192
	ds_read_b128 v[8:11], v221 offset:20480
	s_waitcnt lgkmcnt(4)
	v_mfma_f32_32x32x16_bf16 v[34:49], v[12:15], v[142:145], v[34:49]
	v_mfma_f32_32x32x16_bf16 v[18:33], v[222:225], v[142:145], v[18:33]
	ds_read_b128 v[12:15], v234 offset:8192
	ds_read_b128 v[222:225], v234 offset:20480
	s_waitcnt lgkmcnt(4)
	v_mfma_f32_32x32x16_bf16 v[34:49], v[226:229], v[146:149], v[34:49]
	v_mfma_f32_32x32x16_bf16 v[18:33], v[230:233], v[146:149], v[18:33]
	ds_read_b128 v[226:229], v16 offset:8192
	ds_read_b128 v[230:233], v16 offset:20480
	s_waitcnt lgkmcnt(4)
	v_mfma_f32_32x32x16_bf16 v[34:49], v[4:7], v[150:153], v[34:49]
	v_mfma_f32_32x32x16_bf16 v[18:33], v[8:11], v[150:153], v[18:33]
	s_waitcnt lgkmcnt(2)
	v_mfma_f32_32x32x16_bf16 v[34:49], v[12:15], v[154:157], v[34:49]
	v_mfma_f32_32x32x16_bf16 v[18:33], v[222:225], v[154:157], v[18:33]
	s_waitcnt lgkmcnt(0)
	v_mfma_f32_32x32x16_bf16 v[34:49], v[226:229], v[158:161], v[34:49]
	v_mfma_f32_32x32x16_bf16 v[18:33], v[230:233], v[158:161], v[18:33]
	s_setprio 0

.LBB0_1426:
	s_barrier
	s_andn2_b64 vcc, exec, s[12:13]
	s_cbranch_vccnz .LBB0_1411
	s_nop 0
	v_max3_f32 v4, v18, v19, v20
	v_max3_f32 v4, v4, v21, v22
	v_max3_f32 v4, v4, v23, v24
	v_max3_f32 v4, v4, v25, v26
	v_max3_f32 v4, v4, v27, v28
	v_max3_f32 v4, v4, v29, v30
	v_max3_f32 v4, v4, v31, v32
	v_max3_f32 v4, v4, v33, v34
	v_max3_f32 v4, v4, v35, v36
	v_max3_f32 v4, v4, v37, v38
	v_max3_f32 v4, v4, v39, v40
	v_max3_f32 v4, v4, v41, v42
	v_max3_f32 v4, v4, v43, v44
	v_max3_f32 v4, v4, v45, v46
	v_max3_f32 v4, v4, v47, v48
	v_max_f32_e32 v4, v4, v49
	v_mov_b32_e32 v5, v4
	s_nop 1
	v_permlane32_swap_b32_e32 v4, v5
	v_max_f32_e32 v5, v5, v5
	v_max_f32_e32 v4, v4, v4
	s_cmp_eq_u32 s64, 0
	s_cselect_b64 s[12:13], -1, 0
	s_cmp_lg_u32 s64, 0
	v_max_f32_e32 v4, v4, v5
	s_cbranch_scc0 .Latt_rescale
	v_cmp_lt_f32_e32 vcc, 0x41000000, v4
	s_cmp_lg_u64 vcc, 0
	s_cbranch_scc0 .LBB0_1410
.Latt_rescale:
	v_max_f32_e32 v5, v4, v4
	v_max_f32_e32 v5, 0, v5
	v_cndmask_b32_e64 v4, v5, v4, s[12:13]
	v_exp_f32_e64 v6, -v4
	v_add_f32_e32 v3, v3, v4
	v_pk_add_f32 v[34:35], v[34:35], v[4:5] op_sel_hi:[1,0] neg_lo:[0,1] neg_hi:[0,1]
	v_pk_add_f32 v[18:19], v[18:19], v[4:5] op_sel_hi:[1,0] neg_lo:[0,1] neg_hi:[0,1]
	v_pk_add_f32 v[36:37], v[36:37], v[4:5] op_sel_hi:[1,0] neg_lo:[0,1] neg_hi:[0,1]
	v_pk_add_f32 v[20:21], v[20:21], v[4:5] op_sel_hi:[1,0] neg_lo:[0,1] neg_hi:[0,1]
	v_pk_add_f32 v[38:39], v[38:39], v[4:5] op_sel_hi:[1,0] neg_lo:[0,1] neg_hi:[0,1]
	v_pk_add_f32 v[22:23], v[22:23], v[4:5] op_sel_hi:[1,0] neg_lo:[0,1] neg_hi:[0,1]
	v_pk_add_f32 v[40:41], v[40:41], v[4:5] op_sel_hi:[1,0] neg_lo:[0,1] neg_hi:[0,1]
	v_pk_add_f32 v[24:25], v[24:25], v[4:5] op_sel_hi:[1,0] neg_lo:[0,1] neg_hi:[0,1]
	v_pk_add_f32 v[42:43], v[42:43], v[4:5] op_sel_hi:[1,0] neg_lo:[0,1] neg_hi:[0,1]
	v_pk_add_f32 v[26:27], v[26:27], v[4:5] op_sel_hi:[1,0] neg_lo:[0,1] neg_hi:[0,1]
	v_pk_add_f32 v[44:45], v[44:45], v[4:5] op_sel_hi:[1,0] neg_lo:[0,1] neg_hi:[0,1]
	v_pk_add_f32 v[28:29], v[28:29], v[4:5] op_sel_hi:[1,0] neg_lo:[0,1] neg_hi:[0,1]
	v_pk_add_f32 v[46:47], v[46:47], v[4:5] op_sel_hi:[1,0] neg_lo:[0,1] neg_hi:[0,1]
	v_pk_add_f32 v[30:31], v[30:31], v[4:5] op_sel_hi:[1,0] neg_lo:[0,1] neg_hi:[0,1]
	v_pk_add_f32 v[48:49], v[48:49], v[4:5] op_sel_hi:[1,0] neg_lo:[0,1] neg_hi:[0,1]
	v_pk_add_f32 v[32:33], v[32:33], v[4:5] op_sel_hi:[1,0] neg_lo:[0,1] neg_hi:[0,1]
	v_pk_mul_f32 v[112:113], v[112:113], v[6:7] op_sel_hi:[1,0]
	v_pk_mul_f32 v[110:111], v[110:111], v[6:7] op_sel_hi:[1,0]
	v_pk_mul_f32 v[108:109], v[108:109], v[6:7] op_sel_hi:[1,0]
	v_pk_mul_f32 v[106:107], v[106:107], v[6:7] op_sel_hi:[1,0]
	v_pk_mul_f32 v[104:105], v[104:105], v[6:7] op_sel_hi:[1,0]
	v_pk_mul_f32 v[102:103], v[102:103], v[6:7] op_sel_hi:[1,0]
	v_pk_mul_f32 v[100:101], v[100:101], v[6:7] op_sel_hi:[1,0]
	v_pk_mul_f32 v[98:99], v[98:99], v[6:7] op_sel_hi:[1,0]
	v_pk_mul_f32 v[96:97], v[96:97], v[6:7] op_sel_hi:[1,0]
	v_pk_mul_f32 v[94:95], v[94:95], v[6:7] op_sel_hi:[1,0]
	v_pk_mul_f32 v[92:93], v[92:93], v[6:7] op_sel_hi:[1,0]
	v_pk_mul_f32 v[90:91], v[90:91], v[6:7] op_sel_hi:[1,0]
	v_pk_mul_f32 v[88:89], v[88:89], v[6:7] op_sel_hi:[1,0]
	v_pk_mul_f32 v[86:87], v[86:87], v[6:7] op_sel_hi:[1,0]
	v_pk_mul_f32 v[84:85], v[84:85], v[6:7] op_sel_hi:[1,0]
	v_pk_mul_f32 v[82:83], v[82:83], v[6:7] op_sel_hi:[1,0]
	v_pk_mul_f32 v[80:81], v[80:81], v[6:7] op_sel_hi:[1,0]
	v_pk_mul_f32 v[78:79], v[78:79], v[6:7] op_sel_hi:[1,0]
	v_pk_mul_f32 v[76:77], v[76:77], v[6:7] op_sel_hi:[1,0]
	v_pk_mul_f32 v[74:75], v[74:75], v[6:7] op_sel_hi:[1,0]
	v_pk_mul_f32 v[72:73], v[72:73], v[6:7] op_sel_hi:[1,0]
	v_pk_mul_f32 v[70:71], v[70:71], v[6:7] op_sel_hi:[1,0]
	v_pk_mul_f32 v[68:69], v[68:69], v[6:7] op_sel_hi:[1,0]
	v_pk_mul_f32 v[66:67], v[66:67], v[6:7] op_sel_hi:[1,0]
	v_pk_mul_f32 v[64:65], v[64:65], v[6:7] op_sel_hi:[1,0]
	v_pk_mul_f32 v[62:63], v[62:63], v[6:7] op_sel_hi:[1,0]
	v_pk_mul_f32 v[60:61], v[60:61], v[6:7] op_sel_hi:[1,0]
	v_pk_mul_f32 v[58:59], v[58:59], v[6:7] op_sel_hi:[1,0]
	v_pk_mul_f32 v[56:57], v[56:57], v[6:7] op_sel_hi:[1,0]
	v_pk_mul_f32 v[54:55], v[54:55], v[6:7] op_sel_hi:[1,0]
	v_pk_mul_f32 v[52:53], v[52:53], v[6:7] op_sel_hi:[1,0]
	v_pk_mul_f32 v[50:51], v[50:51], v[6:7] op_sel_hi:[1,0]
	v_mul_f32_e32 v220, v220, v6
	s_branch .LBB0_1410
.LBB0_1433:
	s_and_b64 vcc, exec, s[28:29]
	s_cbranch_vccz .LBB0_1406
	s_barrier
	s_branch .LBB0_1406
	s_nop 0
	s_nop 0
	s_nop 0
	s_nop 0
	s_nop 0
	s_nop 0
	s_nop 0
	s_nop 0
	s_nop 0
	s_nop 0
